# de-phase sleeps: removed before GLU/out-proj GEMMs, halved before mixer phases
# speedup vs baseline: 1.0380x; 1.0030x over previous
.LBB0_326:
	s_or_b64 exec, exec, s[0:1]
	s_lshl_b32 s22, s84, 6
	s_mov_b64 s[0:1], -1
	s_and_b64 vcc, exec, s[8:9]
	s_waitcnt lgkmcnt(0)
	s_barrier
	s_cbranch_vccz .LBB0_500
	v_readlane_b32 s0, v254, 29
	v_readlane_b32 s1, v254, 30
	s_and_b64 vcc, exec, s[0:1]
	s_cbranch_vccz .LBB0_329
	s_sleep 0x7f
.LBB0_329:
	s_lshl_b64 s[0:1], s[22:23], 2
	s_add_u32 s0, s94, s0
	s_addc_u32 s1, s95, s1
	s_add_u32 s8, s0, 0xe881880
	s_addc_u32 s9, s1, 0
	s_barrier
	s_mov_b64 s[0:1], exec
	v_readlane_b32 s20, v252, 3
	v_readlane_b32 s21, v252, 4
	s_and_b64 s[20:21], s[0:1], s[20:21]
	s_mov_b64 exec, s[20:21]
	s_cbranch_execz .LBB0_333
	s_mov_b64 s[24:25], exec
	v_mbcnt_lo_u32_b32 v0, s24, 0
	v_mbcnt_hi_u32_b32 v0, s25, v0
	v_cmp_eq_u32_e32 vcc, 0, v0
	s_and_saveexec_b64 s[20:21], vcc
	s_cbranch_execz .LBB0_332
	s_bcnt1_i32_b64 s6, s[24:25]
	v_mov_b32_e32 v1, s6
	global_atomic_add v1, v145, v1, s[8:9] sc0

.LBB0_500:
	s_and_b64 vcc, exec, s[0:1]
	s_cbranch_vccz .LBB0_798
	v_readlane_b32 s0, v254, 29
	v_readlane_b32 s1, v254, 30
	s_and_b64 vcc, exec, s[0:1]
	s_cbranch_vccz .LBB0_503
	s_sleep 0x7f
.LBB0_503:
	s_lshl_b64 s[0:1], s[22:23], 2
	v_readlane_b32 s6, v254, 37
	s_add_u32 s8, s6, s0
	v_readlane_b32 s0, v254, 38
	s_addc_u32 s9, s0, s1
	v_writelane_b32 v255, s8, 6
	s_barrier
	s_nop 0
	v_writelane_b32 v255, s9, 7
	s_mov_b64 s[0:1], exec
	v_readlane_b32 s8, v252, 3
	v_readlane_b32 s9, v252, 4
	s_and_b64 s[8:9], s[0:1], s[8:9]
	s_mov_b64 exec, s[8:9]
	s_cbranch_execz .LBB0_507
	s_mov_b64 s[20:21], exec
	v_mbcnt_lo_u32_b32 v0, s20, 0
	v_mbcnt_hi_u32_b32 v0, s21, v0
	v_cmp_eq_u32_e32 vcc, 0, v0
	s_and_saveexec_b64 s[8:9], vcc
	s_cbranch_execz .LBB0_506
	s_bcnt1_i32_b64 s6, s[20:21]
	v_readlane_b32 s10, v255, 6
	v_mov_b32_e32 v1, s6
	v_readlane_b32 s11, v255, 7
	s_nop 4
	global_atomic_add v1, v145, v1, s[10:11] sc0

.LBB0_603:
	s_or_b64 exec, exec, s[0:1]
	v_readlane_b32 s0, v254, 29
	v_readlane_b32 s1, v254, 30
	s_andn2_b64 vcc, exec, s[0:1]
	s_waitcnt lgkmcnt(0)
	s_barrier
	s_cbranch_vccnz .LBB0_605
	s_sleep 0x7f
.LBB0_605:
	s_barrier
	s_mov_b64 s[0:1], exec
	v_readlane_b32 s8, v252, 3
	v_readlane_b32 s9, v252, 4
	s_and_b64 s[8:9], s[0:1], s[8:9]
	s_mov_b64 exec, s[8:9]
	s_cbranch_execz .LBB0_609
	s_mov_b64 s[20:21], exec
	v_mbcnt_lo_u32_b32 v0, s20, 0
	v_mbcnt_hi_u32_b32 v0, s21, v0
	v_cmp_eq_u32_e32 vcc, 0, v0
	s_and_saveexec_b64 s[8:9], vcc
	s_cbranch_execz .LBB0_608
	s_bcnt1_i32_b64 s6, s[20:21]
	v_readlane_b32 s10, v255, 6
	v_mov_b32_e32 v1, s6
	v_readlane_b32 s11, v255, 7
	s_nop 4
	global_atomic_add v1, v145, v1, s[10:11] offset:64 sc0

.LBB0_739:
	s_or_b64 exec, exec, s[0:1]
	v_readlane_b32 s0, v254, 29
	v_readlane_b32 s1, v254, 30
	s_waitcnt lgkmcnt(0)
	v_mov_b32_e32 v0, v193
	s_and_b64 vcc, exec, s[0:1]
	s_barrier
	s_cbranch_vccz .LBB0_741
.LBB0_741:
	v_readlane_b32 s0, v254, 49
	v_readlane_b32 s1, v254, 50
	s_andn2_b64 vcc, exec, s[0:1]
	s_cbranch_vccnz .LBB0_745
	v_lshlrev_b32_e32 v2, 4, v0
	v_and_b32_e32 v144, 0x70, v2
	v_ashrrev_i32_e32 v2, 1, v0
	v_bfe_u32 v1, v0, 5, 1
	v_readlane_b32 s8, v254, 25
	v_and_b32_e32 v4, 0xffffffc0, v2
	v_lshlrev_b32_e32 v3, 3, v0
	v_readlane_b32 s9, v254, 26
	s_movk_i32 s6, 0x90
	v_and_or_b32 v5, v0, 31, v4
	v_lshlrev_b32_e32 v2, 4, v1
	v_ashrrev_i32_e32 v137, 3, v0
	v_lshl_add_u64 v[250:251], s[8:9], 0, v[144:145]
	v_mad_u64_u32 v[134:135], s[8:9], v5, s6, v[2:3]
	v_and_b32_e32 v5, 0x5f, v0
	s_lshl_b32 s22, s84, 8
	v_readlane_b32 s36, v252, 59
	v_readlane_b32 s20, v252, 57
	v_mad_u64_u32 v[132:133], s[8:9], v137, s6, v[144:145]
	v_mul_u32_u24_e32 v6, 0x48, v5
	v_ashrrev_i32_e32 v199, 4, v0
	v_lshl_or_b32 v0, v1, 2, v4
	s_movk_i32 s6, 0x210
	s_lshl_b64 s[0:1], s[22:23], 2
	v_readlane_b32 s40, v252, 63
	v_readlane_b32 s21, v252, 58
	v_lshlrev_b32_e32 v6, 1, v6
	v_and_b32_e32 v136, 0x78, v3
	v_mul_i32_i24_e32 v1, 0xffffff74, v5
	v_mul_lo_u32 v163, v199, s6
	v_mul_lo_u32 v0, v0, s6
	v_readlane_b32 s41, v253, 0
	s_add_u32 s0, s40, s0
	v_lshl_add_u64 v[208:209], s[20:21], 0, v[144:145]
	v_lshlrev_b32_e32 v162, 2, v136
	v_add3_u32 v164, v6, v1, v0
	v_lshl_add_u32 v165, v5, 2, v0
	v_add_u32_e32 v0, 0x2100, v163
	v_lshlrev_b32_e32 v144, 1, v136
	s_addc_u32 s1, s41, s1
	v_add_u32_e32 v133, v6, v2
	v_add_u32_e32 v135, 0xd800, v132
	v_add_u32_e32 v166, 16, v199
	v_lshl_add_u64 v[138:139], s[20:21], 0, v[144:145]
	v_add_u32_e32 v167, v162, v0
	v_readlane_b32 s6, v254, 63
	v_readlane_b32 s10, v255, 0
	v_readlane_b32 s12, v254, 60
	v_readlane_b32 s11, v255, 1
	s_mov_b32 s22, 0x10000
	s_mov_b32 s26, 0x1c7e000
	s_mov_b32 s27, 0x8000
	s_mov_b32 s28, 0x18000
	s_mov_b32 s29, 0x4c7f000
	v_readlane_b32 s37, v252, 60
	v_readlane_b32 s38, v252, 61
	v_readlane_b32 s39, v252, 62
	v_readlane_b32 s42, v253, 1
	v_readlane_b32 s43, v253, 2
	v_readlane_b32 s44, v253, 3
	v_readlane_b32 s45, v253, 4
	v_readlane_b32 s46, v253, 5
	v_readlane_b32 s47, v253, 6
	v_readlane_b32 s48, v253, 7
	v_readlane_b32 s49, v253, 8
	v_readlane_b32 s50, v253, 9
	v_readlane_b32 s51, v253, 10

.LBB0_798:
	v_readlane_b32 s0, v254, 29
	v_readlane_b32 s1, v254, 30
	v_mov_b32_e32 v0, v193
	s_andn2_b64 vcc, exec, s[0:1]
	s_cbranch_vccnz .LBB0_800
.LBB0_800:
	v_readlane_b32 s0, v254, 51
	v_readlane_b32 s1, v254, 52
	s_andn2_b64 vcc, exec, s[0:1]
	s_cbranch_vccnz .LBB0_804
	v_lshlrev_b32_e32 v2, 4, v0
	v_readlane_b32 s0, v254, 27
	v_and_b32_e32 v144, 0x70, v2
	v_readlane_b32 s1, v254, 28
	v_ashrrev_i32_e32 v2, 1, v0
	v_bfe_u32 v1, v0, 5, 1
	v_lshl_add_u64 v[146:147], s[0:1], 0, v[144:145]
	v_readlane_b32 s0, v254, 23
	v_and_b32_e32 v4, 0xffffffc0, v2
	v_ashrrev_i32_e32 v137, 3, v0
	v_lshlrev_b32_e32 v3, 3, v0
	v_readlane_b32 s1, v254, 24
	s_movk_i32 s6, 0x90
	v_and_or_b32 v5, v0, 31, v4
	v_lshlrev_b32_e32 v2, 4, v1
	v_lshl_add_u64 v[190:191], s[0:1], 0, v[144:145]
	v_mad_u64_u32 v[132:133], s[0:1], v137, s6, v[144:145]
	v_mad_u64_u32 v[134:135], s[0:1], v5, s6, v[2:3]
	v_and_b32_e32 v5, 0x5f, v0
	v_mul_u32_u24_e32 v6, 0x48, v5
	v_ashrrev_i32_e32 v149, 4, v0
	v_lshl_or_b32 v0, v1, 2, v4
	s_movk_i32 s0, 0x210
	v_lshlrev_b32_e32 v6, 1, v6
	v_and_b32_e32 v136, 0x78, v3
	v_mul_i32_i24_e32 v1, 0xffffff74, v5
	v_mul_lo_u32 v161, v149, s0
	v_mul_lo_u32 v0, v0, s0
	v_readlane_b32 s36, v252, 5
	v_lshlrev_b32_e32 v160, 2, v136
	v_add3_u32 v162, v6, v1, v0
	v_lshl_add_u32 v163, v5, 2, v0
	v_add_u32_e32 v0, 0x2100, v161
	v_readlane_b32 s38, v252, 7
	v_readlane_b32 s28, v255, 3
	v_add_u32_e32 v133, v6, v2
	v_add_u32_e32 v135, 0xd800, v132
	v_add_u32_e32 v164, 16, v149
	v_add_u32_e32 v165, v160, v0
	v_readlane_b32 s6, v254, 63
	v_readlane_b32 s8, v255, 0
	v_readlane_b32 s9, v254, 60
	v_readlane_b32 s37, v252, 6
	v_readlane_b32 s24, v255, 2
	v_readlane_b32 s11, v255, 1
	s_mov_b32 s25, 0x10000
	s_mov_b32 s26, 0x20000
	s_mov_b32 s27, 0x30000
	v_readlane_b32 s29, v255, 4
	v_readlane_b32 s38, v255, 5
	v_readlane_b32 s39, v252, 8
	v_readlane_b32 s40, v252, 9
	v_readlane_b32 s41, v252, 10
	v_readlane_b32 s42, v252, 11
	v_readlane_b32 s43, v252, 12
	v_readlane_b32 s44, v252, 13
	v_readlane_b32 s45, v252, 14
	v_readlane_b32 s46, v252, 15
	v_readlane_b32 s47, v252, 16
	v_readlane_b32 s48, v252, 17
	v_readlane_b32 s49, v252, 18
	v_readlane_b32 s50, v252, 19
	v_readlane_b32 s51, v252, 20
